# stick-breaking q read in place from proj (0.125 folded exactly into the log2e multiply): the DQ copy and its traffic removed
# baseline (speedup 1.0000x reference)
.LBB0_358:
	s_or_b64 exec, exec, s[0:1]
	s_lshr_b32 s3, s2, 6
	s_and_b32 s0, s2, 63
	s_sub_i32 s12, 63, s0
	v_readlane_b32 s0, v253, 31
	v_and_b32_e32 v152, 31, v186
	v_bfe_u32 v153, v186, 5, 1
	s_lshl_b32 s1, s0, 2
	s_add_i32 s1, s1, s3
	s_lshl_b32 s1, s1, 18
	s_add_u32 s40, s16, s1
	s_addc_u32 s41, s17, 0
	s_add_u32 s42, s14, s1
	s_addc_u32 s43, s15, 0
	s_lshl_b32 s1, s0, 10
	s_lshl_b32 s4, s12, 5
	s_add_i32 s1, s1, s4
	v_add_u32_e32 v154, s1, v152
	v_mul_u32_u24_e32 v155, s66, v154
	v_lshl_add_u32 v155, v153, 4, v155
	s_lshl_b32 s1, s3, 7
	s_add_u32 s4, s54, s1
	s_addc_u32 s5, s55, 0
	s_add_u32 s4, s4, 0xa001e30
	s_addc_u32 s5, s5, 0
	global_load_dwordx4 v[48:51], v155, s[4:5]
	global_load_dwordx4 v[52:55], v155, s[4:5] offset:32
	global_load_dwordx4 v[56:59], v155, s[4:5] offset:64
	global_load_dwordx4 v[60:63], v155, s[4:5] offset:96
	v_and_b32_e32 v200, 63, v186
	v_lshlrev_b32_e32 v200, 4, v200
	v_lshlrev_b32_e32 v201, 5, v152
	v_lshl_add_u32 v201, v153, 4, v201
	s_lshl_b32 s1, s12, 12
	s_add_u32 s4, s40, s1
	s_addc_u32 s5, s41, 0
	global_load_dwordx4 v[66:69], v200, s[4:5]
	global_load_dwordx4 v[70:73], v200, s[4:5] offset:1024
	global_load_dwordx4 v[74:77], v200, s[4:5] offset:2048
	global_load_dwordx4 v[78:81], v200, s[4:5] offset:3072
	v_xor_b32_e32 v114, 32, v190
	v_lshlrev_b32_e32 v114, 2, v114
	v_lshlrev_b32_e32 v115, 2, v153
	v_sub_u32_e32 v115, v152, v115
	v_sub_u32_e32 v116, 1, v153
	v_sub_u32_e32 v116, 0, v116
	v_lshlrev_b32_e32 v156, 13, v154
	v_lshl_add_u32 v156, v153, 4, v156
	s_lshl_b32 s1, s3, 8
	s_add_i32 s1, s1, 0x1800
	v_add_u32_e32 v156, s1, v156
	s_add_u32 s4, s54, 0x20000000
	s_addc_u32 s5, s55, 0
	v_mov_b32_e32 v161, s5
	v_add_co_u32_e32 v160, vcc, s4, v156
	s_nop 1
	v_addc_co_u32_e32 v161, vcc, 0, v161, vcc
	v_mov_b32_e32 v127, 0
	v_mov_b32_e32 v0, 0
	v_mov_b32_e32 v1, 0
	v_mov_b32_e32 v2, 0
	v_mov_b32_e32 v3, 0
	v_mov_b32_e32 v4, 0
	v_mov_b32_e32 v5, 0
	v_mov_b32_e32 v6, 0
	v_mov_b32_e32 v7, 0
	v_mov_b32_e32 v8, 0
	v_mov_b32_e32 v9, 0
	v_mov_b32_e32 v10, 0
	v_mov_b32_e32 v11, 0
	v_mov_b32_e32 v12, 0
	v_mov_b32_e32 v13, 0
	v_mov_b32_e32 v14, 0
	v_mov_b32_e32 v15, 0
	v_mov_b32_e32 v16, 0
	v_mov_b32_e32 v17, 0
	v_mov_b32_e32 v18, 0
	v_mov_b32_e32 v19, 0
	v_mov_b32_e32 v20, 0
	v_mov_b32_e32 v21, 0
	v_mov_b32_e32 v22, 0
	v_mov_b32_e32 v23, 0
	v_mov_b32_e32 v24, 0
	v_mov_b32_e32 v25, 0
	v_mov_b32_e32 v26, 0
	v_mov_b32_e32 v27, 0
	v_mov_b32_e32 v28, 0
	v_mov_b32_e32 v29, 0
	v_mov_b32_e32 v30, 0
	v_mov_b32_e32 v31, 0
	s_sub_i32 s0, s12, 1
	s_max_i32 s0, s0, 0
	s_lshl_b32 s0, s0, 12
	s_add_u32 s2, s40, s0
	s_addc_u32 s3, s41, 0
	s_lshl_b32 s0, s12, 12
	s_add_u32 s18, s42, s0
	s_addc_u32 s19, s43, 0
	s_waitcnt vmcnt(0)
	global_load_dwordx4 v[82:85], v200, s[2:3]
	global_load_dwordx4 v[86:89], v200, s[2:3] offset:1024
	global_load_dwordx4 v[90:93], v200, s[2:3] offset:2048
	global_load_dwordx4 v[94:97], v200, s[2:3] offset:3072
	global_load_dwordx4 v[98:101], v201, s[18:19]
	global_load_dwordx4 v[102:105], v201, s[18:19] offset:1024
	global_load_dwordx4 v[106:109], v201, s[18:19] offset:2048
	global_load_dwordx4 v[110:113], v201, s[18:19] offset:3072
	v_mfma_f32_32x32x16_bf16 v[32:47], v[66:69], v[48:51], 0
	v_mfma_f32_32x32x16_bf16 v[32:47], v[70:73], v[52:55], v[32:47]
	v_mfma_f32_32x32x16_bf16 v[32:47], v[74:77], v[56:59], v[32:47]
	v_mfma_f32_32x32x16_bf16 v[32:47], v[78:81], v[60:63], v[32:47]
	s_nop 11
	v_mul_f32_e32 v44, 0x3e38aa3b, v44
	v_mul_f32_e32 v45, 0x3e38aa3b, v45
	v_mul_f32_e32 v46, 0x3e38aa3b, v46
	v_mul_f32_e32 v47, 0x3e38aa3b, v47
	v_exp_f32_e64 v152, -|v44|
	v_exp_f32_e64 v153, -|v45|
	v_exp_f32_e64 v154, -|v46|
	v_exp_f32_e64 v155, -|v47|
	v_max_f32_e32 v140, 0, v44
	v_max_f32_e32 v141, 0, v45
	v_max_f32_e32 v142, 0, v46
	v_max_f32_e32 v143, 0, v47
	v_add_f32_e32 v152, 1.0, v152
	v_add_f32_e32 v153, 1.0, v153
	v_add_f32_e32 v154, 1.0, v154
	v_add_f32_e32 v155, 1.0, v155
	v_log_f32_e32 v152, v152
	v_log_f32_e32 v153, v153
	v_log_f32_e32 v154, v154
	v_log_f32_e32 v155, v155
	s_nop 0
	v_add_f32_e32 v140, v140, v152
	v_add_f32_e32 v141, v141, v153
	v_add_f32_e32 v142, v142, v154
	v_add_f32_e32 v143, v143, v155
	v_cmp_lt_i32_e64 s[0:1], 24, v115
	v_cmp_lt_i32_e64 s[2:3], 25, v115
	v_cmp_lt_i32_e64 s[4:5], 26, v115
	v_cmp_lt_i32_e64 s[6:7], 27, v115
	s_nop 1
	v_cndmask_b32_e64 v140, 0, v140, s[0:1]
	v_cndmask_b32_e64 v141, 0, v141, s[2:3]
	v_cndmask_b32_e64 v142, 0, v142, s[4:5]
	v_cndmask_b32_e64 v143, 0, v143, s[6:7]
	v_add_f32_e32 v152, v140, v141
	v_add_f32_e32 v153, v142, v143
	v_add_f32_e32 v122, v152, v153
	ds_bpermute_b32 v126, v114, v122
	v_mul_f32_e32 v40, 0x3e38aa3b, v40
	v_mul_f32_e32 v41, 0x3e38aa3b, v41
	v_mul_f32_e32 v42, 0x3e38aa3b, v42
	v_mul_f32_e32 v43, 0x3e38aa3b, v43
	v_exp_f32_e64 v152, -|v40|
	v_exp_f32_e64 v153, -|v41|
	v_exp_f32_e64 v154, -|v42|
	v_exp_f32_e64 v155, -|v43|
	v_max_f32_e32 v136, 0, v40
	v_max_f32_e32 v137, 0, v41
	v_max_f32_e32 v138, 0, v42
	v_max_f32_e32 v139, 0, v43
	v_add_f32_e32 v152, 1.0, v152
	v_add_f32_e32 v153, 1.0, v153
	v_add_f32_e32 v154, 1.0, v154
	v_add_f32_e32 v155, 1.0, v155
	v_log_f32_e32 v152, v152
	v_log_f32_e32 v153, v153
	v_log_f32_e32 v154, v154
	v_log_f32_e32 v155, v155
	s_nop 0
	v_add_f32_e32 v136, v136, v152
	v_add_f32_e32 v137, v137, v153
	v_add_f32_e32 v138, v138, v154
	v_add_f32_e32 v139, v139, v155
	v_cmp_lt_i32_e64 s[0:1], 16, v115
	v_cmp_lt_i32_e64 s[2:3], 17, v115
	v_cmp_lt_i32_e64 s[4:5], 18, v115
	v_cmp_lt_i32_e64 s[6:7], 19, v115
	s_nop 1
	v_cndmask_b32_e64 v136, 0, v136, s[0:1]
	v_cndmask_b32_e64 v137, 0, v137, s[2:3]
	v_cndmask_b32_e64 v138, 0, v138, s[4:5]
	v_cndmask_b32_e64 v139, 0, v139, s[6:7]
	v_add_f32_e32 v152, v136, v137
	v_add_f32_e32 v153, v138, v139
	v_add_f32_e32 v121, v152, v153
	ds_bpermute_b32 v125, v114, v121
	v_mul_f32_e32 v36, 0x3e38aa3b, v36
	v_mul_f32_e32 v37, 0x3e38aa3b, v37
	v_mul_f32_e32 v38, 0x3e38aa3b, v38
	v_mul_f32_e32 v39, 0x3e38aa3b, v39
	v_exp_f32_e64 v152, -|v36|
	v_exp_f32_e64 v153, -|v37|
	v_exp_f32_e64 v154, -|v38|
	v_exp_f32_e64 v155, -|v39|
	v_max_f32_e32 v132, 0, v36
	v_max_f32_e32 v133, 0, v37
	v_max_f32_e32 v134, 0, v38
	v_max_f32_e32 v135, 0, v39
	v_add_f32_e32 v152, 1.0, v152
	v_add_f32_e32 v153, 1.0, v153
	v_add_f32_e32 v154, 1.0, v154
	v_add_f32_e32 v155, 1.0, v155
	v_log_f32_e32 v152, v152
	v_log_f32_e32 v153, v153
	v_log_f32_e32 v154, v154
	v_log_f32_e32 v155, v155
	s_nop 0
	v_add_f32_e32 v132, v132, v152
	v_add_f32_e32 v133, v133, v153
	v_add_f32_e32 v134, v134, v154
	v_add_f32_e32 v135, v135, v155
	v_cmp_lt_i32_e64 s[0:1], 8, v115
	v_cmp_lt_i32_e64 s[2:3], 9, v115
	v_cmp_lt_i32_e64 s[4:5], 10, v115
	v_cmp_lt_i32_e64 s[6:7], 11, v115
	s_nop 1
	v_cndmask_b32_e64 v132, 0, v132, s[0:1]
	v_cndmask_b32_e64 v133, 0, v133, s[2:3]
	v_cndmask_b32_e64 v134, 0, v134, s[4:5]
	v_cndmask_b32_e64 v135, 0, v135, s[6:7]
	v_add_f32_e32 v152, v132, v133
	v_add_f32_e32 v153, v134, v135
	v_add_f32_e32 v120, v152, v153
	ds_bpermute_b32 v124, v114, v120
	v_mul_f32_e32 v32, 0x3e38aa3b, v32
	v_mul_f32_e32 v33, 0x3e38aa3b, v33
	v_mul_f32_e32 v34, 0x3e38aa3b, v34
	v_mul_f32_e32 v35, 0x3e38aa3b, v35
	v_exp_f32_e64 v152, -|v32|
	v_exp_f32_e64 v153, -|v33|
	v_exp_f32_e64 v154, -|v34|
	v_exp_f32_e64 v155, -|v35|
	v_max_f32_e32 v128, 0, v32
	v_max_f32_e32 v129, 0, v33
	v_max_f32_e32 v130, 0, v34
	v_max_f32_e32 v131, 0, v35
	v_add_f32_e32 v152, 1.0, v152
	v_add_f32_e32 v153, 1.0, v153
	v_add_f32_e32 v154, 1.0, v154
	v_add_f32_e32 v155, 1.0, v155
	v_log_f32_e32 v152, v152
	v_log_f32_e32 v153, v153
	v_log_f32_e32 v154, v154
	v_log_f32_e32 v155, v155
	s_nop 0
	v_add_f32_e32 v128, v128, v152
	v_add_f32_e32 v129, v129, v153
	v_add_f32_e32 v130, v130, v154
	v_add_f32_e32 v131, v131, v155
	v_cmp_lt_i32_e64 s[0:1], 0, v115
	v_cmp_lt_i32_e64 s[2:3], 1, v115
	v_cmp_lt_i32_e64 s[4:5], 2, v115
	v_cmp_lt_i32_e64 s[6:7], 3, v115
	s_nop 1
	v_cndmask_b32_e64 v128, 0, v128, s[0:1]
	v_cndmask_b32_e64 v129, 0, v129, s[2:3]
	v_cndmask_b32_e64 v130, 0, v130, s[4:5]
	v_cndmask_b32_e64 v131, 0, v131, s[6:7]
	v_add_f32_e32 v152, v128, v129
	v_add_f32_e32 v153, v130, v131
	v_add_f32_e32 v119, v152, v153
	ds_bpermute_b32 v123, v114, v119
	s_waitcnt lgkmcnt(3)
	v_and_b32_e32 v152, v116, v126
	v_add_f32_e32 v153, v122, v126
	v_sub_f32_e32 v199, v127, v152
	v_sub_f32_e32 v127, v127, v153
	v_sub_f32_e32 v159, v199, v143
	v_sub_f32_e32 v158, v159, v142
	v_sub_f32_e32 v157, v158, v141
	v_sub_f32_e32 v156, v157, v140
	v_cmp_lt_i32_e64 s[0:1], 24, v115
	v_cmp_lt_i32_e64 s[2:3], 25, v115
	v_cmp_lt_i32_e64 s[4:5], 26, v115
	v_cmp_lt_i32_e64 s[6:7], 27, v115
	v_add_f32_e32 v44, v44, v156
	v_add_f32_e32 v45, v45, v157
	v_add_f32_e32 v46, v46, v158
	v_add_f32_e32 v47, v47, v159
	v_exp_f32_e32 v44, v44
	v_exp_f32_e32 v45, v45
	v_exp_f32_e32 v46, v46
	v_exp_f32_e32 v47, v47
	s_nop 0
	v_cndmask_b32_e64 v44, 0, v44, s[0:1]
	v_cndmask_b32_e64 v45, 0, v45, s[2:3]
	v_cndmask_b32_e64 v46, 0, v46, s[4:5]
	v_cndmask_b32_e64 v47, 0, v47, s[6:7]
	s_waitcnt lgkmcnt(2)
	v_and_b32_e32 v152, v116, v125
	v_add_f32_e32 v153, v121, v125
	v_sub_f32_e32 v199, v127, v152
	v_sub_f32_e32 v127, v127, v153
	v_sub_f32_e32 v159, v199, v139
	v_sub_f32_e32 v158, v159, v138
	v_sub_f32_e32 v157, v158, v137
	v_sub_f32_e32 v156, v157, v136
	v_cmp_lt_i32_e64 s[0:1], 16, v115
	v_cmp_lt_i32_e64 s[2:3], 17, v115
	v_cmp_lt_i32_e64 s[4:5], 18, v115
	v_cmp_lt_i32_e64 s[6:7], 19, v115
	v_add_f32_e32 v40, v40, v156
	v_add_f32_e32 v41, v41, v157
	v_add_f32_e32 v42, v42, v158
	v_add_f32_e32 v43, v43, v159
	v_exp_f32_e32 v40, v40
	v_exp_f32_e32 v41, v41
	v_exp_f32_e32 v42, v42
	v_exp_f32_e32 v43, v43
	s_nop 0
	v_cndmask_b32_e64 v40, 0, v40, s[0:1]
	v_cndmask_b32_e64 v41, 0, v41, s[2:3]
	v_cndmask_b32_e64 v42, 0, v42, s[4:5]
	v_cndmask_b32_e64 v43, 0, v43, s[6:7]
	s_waitcnt lgkmcnt(1)
	v_and_b32_e32 v152, v116, v124
	v_add_f32_e32 v153, v120, v124
	v_sub_f32_e32 v199, v127, v152
	v_sub_f32_e32 v127, v127, v153
	v_sub_f32_e32 v159, v199, v135
	v_sub_f32_e32 v158, v159, v134
	v_sub_f32_e32 v157, v158, v133
	v_sub_f32_e32 v156, v157, v132
	v_cmp_lt_i32_e64 s[0:1], 8, v115
	v_cmp_lt_i32_e64 s[2:3], 9, v115
	v_cmp_lt_i32_e64 s[4:5], 10, v115
	v_cmp_lt_i32_e64 s[6:7], 11, v115
	v_add_f32_e32 v36, v36, v156
	v_add_f32_e32 v37, v37, v157
	v_add_f32_e32 v38, v38, v158
	v_add_f32_e32 v39, v39, v159
	v_exp_f32_e32 v36, v36
	v_exp_f32_e32 v37, v37
	v_exp_f32_e32 v38, v38
	v_exp_f32_e32 v39, v39
	s_nop 0
	v_cndmask_b32_e64 v36, 0, v36, s[0:1]
	v_cndmask_b32_e64 v37, 0, v37, s[2:3]
	v_cndmask_b32_e64 v38, 0, v38, s[4:5]
	v_cndmask_b32_e64 v39, 0, v39, s[6:7]
	s_waitcnt lgkmcnt(0)
	v_and_b32_e32 v152, v116, v123
	v_add_f32_e32 v153, v119, v123
	v_sub_f32_e32 v199, v127, v152
	v_sub_f32_e32 v127, v127, v153
	v_sub_f32_e32 v159, v199, v131
	v_sub_f32_e32 v158, v159, v130
	v_sub_f32_e32 v157, v158, v129
	v_sub_f32_e32 v156, v157, v128
	v_cmp_lt_i32_e64 s[0:1], 0, v115
	v_cmp_lt_i32_e64 s[2:3], 1, v115
	v_cmp_lt_i32_e64 s[4:5], 2, v115
	v_cmp_lt_i32_e64 s[6:7], 3, v115
	v_add_f32_e32 v32, v32, v156
	v_add_f32_e32 v33, v33, v157
	v_add_f32_e32 v34, v34, v158
	v_add_f32_e32 v35, v35, v159
	v_exp_f32_e32 v32, v32
	v_exp_f32_e32 v33, v33
	v_exp_f32_e32 v34, v34
	v_exp_f32_e32 v35, v35
	s_nop 0
	v_cndmask_b32_e64 v32, 0, v32, s[0:1]
	v_cndmask_b32_e64 v33, 0, v33, s[2:3]
	v_cndmask_b32_e64 v34, 0, v34, s[4:5]
	v_cndmask_b32_e64 v35, 0, v35, s[6:7]
	v_cvt_pk_bf16_f32 v144, v32, v33
	v_cvt_pk_bf16_f32 v145, v34, v35
	v_cvt_pk_bf16_f32 v146, v36, v37
	v_cvt_pk_bf16_f32 v147, v38, v39
	v_cvt_pk_bf16_f32 v148, v40, v41
	v_cvt_pk_bf16_f32 v149, v42, v43
	v_cvt_pk_bf16_f32 v150, v44, v45
	v_cvt_pk_bf16_f32 v151, v46, v47
	v_cmp_gt_f32_e32 vcc, 0xc3177ba5, v127
	s_waitcnt vmcnt(0)
	v_mfma_f32_32x32x16_bf16 v[16:31], v[98:101], v[144:147], v[16:31]
	v_mfma_f32_32x32x16_bf16 v[0:15], v[102:105], v[144:147], v[0:15]
	v_mfma_f32_32x32x16_bf16 v[16:31], v[106:109], v[148:151], v[16:31]
	v_mfma_f32_32x32x16_bf16 v[0:15], v[110:113], v[148:151], v[0:15]
	s_cmp_eq_u64 vcc, exec
	s_cselect_b32 s0, 1, 0
	s_cmp_eq_u32 s12, 0
	s_cselect_b32 s1, 1, 0
	s_or_b32 s0, s0, s1
	s_sub_i32 s12, s12, 1
	s_cmp_lg_u32 s0, 0
	s_cbranch_scc1 .Lsb_done
.Lsb_loop:
	s_sub_i32 s0, s12, 1
	s_max_i32 s0, s0, 0
	s_lshl_b32 s0, s0, 12
	s_add_u32 s2, s40, s0
	s_addc_u32 s3, s41, 0
	s_lshl_b32 s0, s12, 12
	s_add_u32 s18, s42, s0
	s_addc_u32 s19, s43, 0
	s_waitcnt vmcnt(0)
	global_load_dwordx4 v[66:69], v200, s[2:3]
	global_load_dwordx4 v[70:73], v200, s[2:3] offset:1024
	global_load_dwordx4 v[74:77], v200, s[2:3] offset:2048
	global_load_dwordx4 v[78:81], v200, s[2:3] offset:3072
	global_load_dwordx4 v[98:101], v201, s[18:19]
	global_load_dwordx4 v[102:105], v201, s[18:19] offset:1024
	global_load_dwordx4 v[106:109], v201, s[18:19] offset:2048
	global_load_dwordx4 v[110:113], v201, s[18:19] offset:3072
	v_mfma_f32_32x32x16_bf16 v[32:47], v[82:85], v[48:51], 0
	v_mfma_f32_32x32x16_bf16 v[32:47], v[86:89], v[52:55], v[32:47]
	v_mfma_f32_32x32x16_bf16 v[32:47], v[90:93], v[56:59], v[32:47]
	v_mfma_f32_32x32x16_bf16 v[32:47], v[94:97], v[60:63], v[32:47]
	s_nop 11
	v_mul_f32_e32 v44, 0x3e38aa3b, v44
	v_mul_f32_e32 v45, 0x3e38aa3b, v45
	v_mul_f32_e32 v46, 0x3e38aa3b, v46
	v_mul_f32_e32 v47, 0x3e38aa3b, v47
	v_exp_f32_e64 v152, -|v44|
	v_exp_f32_e64 v153, -|v45|
	v_exp_f32_e64 v154, -|v46|
	v_exp_f32_e64 v155, -|v47|
	v_max_f32_e32 v140, 0, v44
	v_max_f32_e32 v141, 0, v45
	v_max_f32_e32 v142, 0, v46
	v_max_f32_e32 v143, 0, v47
	v_add_f32_e32 v152, 1.0, v152
	v_add_f32_e32 v153, 1.0, v153
	v_add_f32_e32 v154, 1.0, v154
	v_add_f32_e32 v155, 1.0, v155
	v_log_f32_e32 v152, v152
	v_log_f32_e32 v153, v153
	v_log_f32_e32 v154, v154
	v_log_f32_e32 v155, v155
	s_nop 0
	v_add_f32_e32 v140, v140, v152
	v_add_f32_e32 v141, v141, v153
	v_add_f32_e32 v142, v142, v154
	v_add_f32_e32 v143, v143, v155
	v_add_f32_e32 v152, v140, v141
	v_add_f32_e32 v153, v142, v143
	v_add_f32_e32 v122, v152, v153
	ds_bpermute_b32 v126, v114, v122
	v_mul_f32_e32 v40, 0x3e38aa3b, v40
	v_mul_f32_e32 v41, 0x3e38aa3b, v41
	v_mul_f32_e32 v42, 0x3e38aa3b, v42
	v_mul_f32_e32 v43, 0x3e38aa3b, v43
	v_exp_f32_e64 v152, -|v40|
	v_exp_f32_e64 v153, -|v41|
	v_exp_f32_e64 v154, -|v42|
	v_exp_f32_e64 v155, -|v43|
	v_max_f32_e32 v136, 0, v40
	v_max_f32_e32 v137, 0, v41
	v_max_f32_e32 v138, 0, v42
	v_max_f32_e32 v139, 0, v43
	v_add_f32_e32 v152, 1.0, v152
	v_add_f32_e32 v153, 1.0, v153
	v_add_f32_e32 v154, 1.0, v154
	v_add_f32_e32 v155, 1.0, v155
	v_log_f32_e32 v152, v152
	v_log_f32_e32 v153, v153
	v_log_f32_e32 v154, v154
	v_log_f32_e32 v155, v155
	s_nop 0
	v_add_f32_e32 v136, v136, v152
	v_add_f32_e32 v137, v137, v153
	v_add_f32_e32 v138, v138, v154
	v_add_f32_e32 v139, v139, v155
	v_add_f32_e32 v152, v136, v137
	v_add_f32_e32 v153, v138, v139
	v_add_f32_e32 v121, v152, v153
	ds_bpermute_b32 v125, v114, v121
	v_mul_f32_e32 v36, 0x3e38aa3b, v36
	v_mul_f32_e32 v37, 0x3e38aa3b, v37
	v_mul_f32_e32 v38, 0x3e38aa3b, v38
	v_mul_f32_e32 v39, 0x3e38aa3b, v39
	v_exp_f32_e64 v152, -|v36|
	v_exp_f32_e64 v153, -|v37|
	v_exp_f32_e64 v154, -|v38|
	v_exp_f32_e64 v155, -|v39|
	v_max_f32_e32 v132, 0, v36
	v_max_f32_e32 v133, 0, v37
	v_max_f32_e32 v134, 0, v38
	v_max_f32_e32 v135, 0, v39
	v_add_f32_e32 v152, 1.0, v152
	v_add_f32_e32 v153, 1.0, v153
	v_add_f32_e32 v154, 1.0, v154
	v_add_f32_e32 v155, 1.0, v155
	v_log_f32_e32 v152, v152
	v_log_f32_e32 v153, v153
	v_log_f32_e32 v154, v154
	v_log_f32_e32 v155, v155
	s_nop 0
	v_add_f32_e32 v132, v132, v152
	v_add_f32_e32 v133, v133, v153
	v_add_f32_e32 v134, v134, v154
	v_add_f32_e32 v135, v135, v155
	v_add_f32_e32 v152, v132, v133
	v_add_f32_e32 v153, v134, v135
	v_add_f32_e32 v120, v152, v153
	ds_bpermute_b32 v124, v114, v120
	v_mul_f32_e32 v32, 0x3e38aa3b, v32
	v_mul_f32_e32 v33, 0x3e38aa3b, v33
	v_mul_f32_e32 v34, 0x3e38aa3b, v34
	v_mul_f32_e32 v35, 0x3e38aa3b, v35
	v_exp_f32_e64 v152, -|v32|
	v_exp_f32_e64 v153, -|v33|
	v_exp_f32_e64 v154, -|v34|
	v_exp_f32_e64 v155, -|v35|
	v_max_f32_e32 v128, 0, v32
	v_max_f32_e32 v129, 0, v33
	v_max_f32_e32 v130, 0, v34
	v_max_f32_e32 v131, 0, v35
	v_add_f32_e32 v152, 1.0, v152
	v_add_f32_e32 v153, 1.0, v153
	v_add_f32_e32 v154, 1.0, v154
	v_add_f32_e32 v155, 1.0, v155
	v_log_f32_e32 v152, v152
	v_log_f32_e32 v153, v153
	v_log_f32_e32 v154, v154
	v_log_f32_e32 v155, v155
	s_nop 0
	v_add_f32_e32 v128, v128, v152
	v_add_f32_e32 v129, v129, v153
	v_add_f32_e32 v130, v130, v154
	v_add_f32_e32 v131, v131, v155
	v_add_f32_e32 v152, v128, v129
	v_add_f32_e32 v153, v130, v131
	v_add_f32_e32 v119, v152, v153
	ds_bpermute_b32 v123, v114, v119
	s_waitcnt lgkmcnt(3)
	v_and_b32_e32 v152, v116, v126
	v_add_f32_e32 v153, v122, v126
	v_sub_f32_e32 v199, v127, v152
	v_sub_f32_e32 v127, v127, v153
	v_sub_f32_e32 v159, v199, v143
	v_sub_f32_e32 v158, v159, v142
	v_sub_f32_e32 v157, v158, v141
	v_sub_f32_e32 v156, v157, v140
	v_add_f32_e32 v44, v44, v156
	v_add_f32_e32 v45, v45, v157
	v_add_f32_e32 v46, v46, v158
	v_add_f32_e32 v47, v47, v159
	v_exp_f32_e32 v44, v44
	v_exp_f32_e32 v45, v45
	v_exp_f32_e32 v46, v46
	v_exp_f32_e32 v47, v47
	s_waitcnt lgkmcnt(2)
	v_and_b32_e32 v152, v116, v125
	v_add_f32_e32 v153, v121, v125
	v_sub_f32_e32 v199, v127, v152
	v_sub_f32_e32 v127, v127, v153
	v_sub_f32_e32 v159, v199, v139
	v_sub_f32_e32 v158, v159, v138
	v_sub_f32_e32 v157, v158, v137
	v_sub_f32_e32 v156, v157, v136
	v_add_f32_e32 v40, v40, v156
	v_add_f32_e32 v41, v41, v157
	v_add_f32_e32 v42, v42, v158
	v_add_f32_e32 v43, v43, v159
	v_exp_f32_e32 v40, v40
	v_exp_f32_e32 v41, v41
	v_exp_f32_e32 v42, v42
	v_exp_f32_e32 v43, v43
	s_waitcnt lgkmcnt(1)
	v_and_b32_e32 v152, v116, v124
	v_add_f32_e32 v153, v120, v124
	v_sub_f32_e32 v199, v127, v152
	v_sub_f32_e32 v127, v127, v153
	v_sub_f32_e32 v159, v199, v135
	v_sub_f32_e32 v158, v159, v134
	v_sub_f32_e32 v157, v158, v133
	v_sub_f32_e32 v156, v157, v132
	v_add_f32_e32 v36, v36, v156
	v_add_f32_e32 v37, v37, v157
	v_add_f32_e32 v38, v38, v158
	v_add_f32_e32 v39, v39, v159
	v_exp_f32_e32 v36, v36
	v_exp_f32_e32 v37, v37
	v_exp_f32_e32 v38, v38
	v_exp_f32_e32 v39, v39
	s_waitcnt lgkmcnt(0)
	v_and_b32_e32 v152, v116, v123
	v_add_f32_e32 v153, v119, v123
	v_sub_f32_e32 v199, v127, v152
	v_sub_f32_e32 v127, v127, v153
	v_sub_f32_e32 v159, v199, v131
	v_sub_f32_e32 v158, v159, v130
	v_sub_f32_e32 v157, v158, v129
	v_sub_f32_e32 v156, v157, v128
	v_add_f32_e32 v32, v32, v156
	v_add_f32_e32 v33, v33, v157
	v_add_f32_e32 v34, v34, v158
	v_add_f32_e32 v35, v35, v159
	v_exp_f32_e32 v32, v32
	v_exp_f32_e32 v33, v33
	v_exp_f32_e32 v34, v34
	v_exp_f32_e32 v35, v35
	v_cvt_pk_bf16_f32 v144, v32, v33
	v_cvt_pk_bf16_f32 v145, v34, v35
	v_cvt_pk_bf16_f32 v146, v36, v37
	v_cvt_pk_bf16_f32 v147, v38, v39
	v_cvt_pk_bf16_f32 v148, v40, v41
	v_cvt_pk_bf16_f32 v149, v42, v43
	v_cvt_pk_bf16_f32 v150, v44, v45
	v_cvt_pk_bf16_f32 v151, v46, v47
	v_cmp_gt_f32_e32 vcc, 0xc3177ba5, v127
	s_waitcnt vmcnt(0)
	v_mfma_f32_32x32x16_bf16 v[16:31], v[98:101], v[144:147], v[16:31]
	v_mfma_f32_32x32x16_bf16 v[0:15], v[102:105], v[144:147], v[0:15]
	v_mfma_f32_32x32x16_bf16 v[16:31], v[106:109], v[148:151], v[16:31]
	v_mfma_f32_32x32x16_bf16 v[0:15], v[110:113], v[148:151], v[0:15]
	s_cmp_eq_u64 vcc, exec
	s_cselect_b32 s0, 1, 0
	s_cmp_eq_u32 s12, 0
	s_cselect_b32 s1, 1, 0
	s_or_b32 s0, s0, s1
	s_sub_i32 s12, s12, 1
	s_cmp_lg_u32 s0, 0
	s_cbranch_scc1 .Lsb_done
	s_sub_i32 s0, s12, 1
	s_max_i32 s0, s0, 0
	s_lshl_b32 s0, s0, 12
	s_add_u32 s2, s40, s0
	s_addc_u32 s3, s41, 0
	s_lshl_b32 s0, s12, 12
	s_add_u32 s18, s42, s0
	s_addc_u32 s19, s43, 0
	s_waitcnt vmcnt(0)
	global_load_dwordx4 v[82:85], v200, s[2:3]
	global_load_dwordx4 v[86:89], v200, s[2:3] offset:1024
	global_load_dwordx4 v[90:93], v200, s[2:3] offset:2048
	global_load_dwordx4 v[94:97], v200, s[2:3] offset:3072
	global_load_dwordx4 v[98:101], v201, s[18:19]
	global_load_dwordx4 v[102:105], v201, s[18:19] offset:1024
	global_load_dwordx4 v[106:109], v201, s[18:19] offset:2048
	global_load_dwordx4 v[110:113], v201, s[18:19] offset:3072
	v_mfma_f32_32x32x16_bf16 v[32:47], v[66:69], v[48:51], 0
	v_mfma_f32_32x32x16_bf16 v[32:47], v[70:73], v[52:55], v[32:47]
	v_mfma_f32_32x32x16_bf16 v[32:47], v[74:77], v[56:59], v[32:47]
	v_mfma_f32_32x32x16_bf16 v[32:47], v[78:81], v[60:63], v[32:47]
	s_nop 11
	v_mul_f32_e32 v44, 0x3e38aa3b, v44
	v_mul_f32_e32 v45, 0x3e38aa3b, v45
	v_mul_f32_e32 v46, 0x3e38aa3b, v46
	v_mul_f32_e32 v47, 0x3e38aa3b, v47
	v_exp_f32_e64 v152, -|v44|
	v_exp_f32_e64 v153, -|v45|
	v_exp_f32_e64 v154, -|v46|
	v_exp_f32_e64 v155, -|v47|
	v_max_f32_e32 v140, 0, v44
	v_max_f32_e32 v141, 0, v45
	v_max_f32_e32 v142, 0, v46
	v_max_f32_e32 v143, 0, v47
	v_add_f32_e32 v152, 1.0, v152
	v_add_f32_e32 v153, 1.0, v153
	v_add_f32_e32 v154, 1.0, v154
	v_add_f32_e32 v155, 1.0, v155
	v_log_f32_e32 v152, v152
	v_log_f32_e32 v153, v153
	v_log_f32_e32 v154, v154
	v_log_f32_e32 v155, v155
	s_nop 0
	v_add_f32_e32 v140, v140, v152
	v_add_f32_e32 v141, v141, v153
	v_add_f32_e32 v142, v142, v154
	v_add_f32_e32 v143, v143, v155
	v_add_f32_e32 v152, v140, v141
	v_add_f32_e32 v153, v142, v143
	v_add_f32_e32 v122, v152, v153
	ds_bpermute_b32 v126, v114, v122
	v_mul_f32_e32 v40, 0x3e38aa3b, v40
	v_mul_f32_e32 v41, 0x3e38aa3b, v41
	v_mul_f32_e32 v42, 0x3e38aa3b, v42
	v_mul_f32_e32 v43, 0x3e38aa3b, v43
	v_exp_f32_e64 v152, -|v40|
	v_exp_f32_e64 v153, -|v41|
	v_exp_f32_e64 v154, -|v42|
	v_exp_f32_e64 v155, -|v43|
	v_max_f32_e32 v136, 0, v40
	v_max_f32_e32 v137, 0, v41
	v_max_f32_e32 v138, 0, v42
	v_max_f32_e32 v139, 0, v43
	v_add_f32_e32 v152, 1.0, v152
	v_add_f32_e32 v153, 1.0, v153
	v_add_f32_e32 v154, 1.0, v154
	v_add_f32_e32 v155, 1.0, v155
	v_log_f32_e32 v152, v152
	v_log_f32_e32 v153, v153
	v_log_f32_e32 v154, v154
	v_log_f32_e32 v155, v155
	s_nop 0
	v_add_f32_e32 v136, v136, v152
	v_add_f32_e32 v137, v137, v153
	v_add_f32_e32 v138, v138, v154
	v_add_f32_e32 v139, v139, v155
	v_add_f32_e32 v152, v136, v137
	v_add_f32_e32 v153, v138, v139
	v_add_f32_e32 v121, v152, v153
	ds_bpermute_b32 v125, v114, v121
	v_mul_f32_e32 v36, 0x3e38aa3b, v36
	v_mul_f32_e32 v37, 0x3e38aa3b, v37
	v_mul_f32_e32 v38, 0x3e38aa3b, v38
	v_mul_f32_e32 v39, 0x3e38aa3b, v39
	v_exp_f32_e64 v152, -|v36|
	v_exp_f32_e64 v153, -|v37|
	v_exp_f32_e64 v154, -|v38|
	v_exp_f32_e64 v155, -|v39|
	v_max_f32_e32 v132, 0, v36
	v_max_f32_e32 v133, 0, v37
	v_max_f32_e32 v134, 0, v38
	v_max_f32_e32 v135, 0, v39
	v_add_f32_e32 v152, 1.0, v152
	v_add_f32_e32 v153, 1.0, v153
	v_add_f32_e32 v154, 1.0, v154
	v_add_f32_e32 v155, 1.0, v155
	v_log_f32_e32 v152, v152
	v_log_f32_e32 v153, v153
	v_log_f32_e32 v154, v154
	v_log_f32_e32 v155, v155
	s_nop 0
	v_add_f32_e32 v132, v132, v152
	v_add_f32_e32 v133, v133, v153
	v_add_f32_e32 v134, v134, v154
	v_add_f32_e32 v135, v135, v155
	v_add_f32_e32 v152, v132, v133
	v_add_f32_e32 v153, v134, v135
	v_add_f32_e32 v120, v152, v153
	ds_bpermute_b32 v124, v114, v120
	v_mul_f32_e32 v32, 0x3e38aa3b, v32
	v_mul_f32_e32 v33, 0x3e38aa3b, v33
	v_mul_f32_e32 v34, 0x3e38aa3b, v34
	v_mul_f32_e32 v35, 0x3e38aa3b, v35
	v_exp_f32_e64 v152, -|v32|
	v_exp_f32_e64 v153, -|v33|
	v_exp_f32_e64 v154, -|v34|
	v_exp_f32_e64 v155, -|v35|
	v_max_f32_e32 v128, 0, v32
	v_max_f32_e32 v129, 0, v33
	v_max_f32_e32 v130, 0, v34
	v_max_f32_e32 v131, 0, v35
	v_add_f32_e32 v152, 1.0, v152
	v_add_f32_e32 v153, 1.0, v153
	v_add_f32_e32 v154, 1.0, v154
	v_add_f32_e32 v155, 1.0, v155
	v_log_f32_e32 v152, v152
	v_log_f32_e32 v153, v153
	v_log_f32_e32 v154, v154
	v_log_f32_e32 v155, v155
	s_nop 0
	v_add_f32_e32 v128, v128, v152
	v_add_f32_e32 v129, v129, v153
	v_add_f32_e32 v130, v130, v154
	v_add_f32_e32 v131, v131, v155
	v_add_f32_e32 v152, v128, v129
	v_add_f32_e32 v153, v130, v131
	v_add_f32_e32 v119, v152, v153
	ds_bpermute_b32 v123, v114, v119
	s_waitcnt lgkmcnt(3)
	v_and_b32_e32 v152, v116, v126
	v_add_f32_e32 v153, v122, v126
	v_sub_f32_e32 v199, v127, v152
	v_sub_f32_e32 v127, v127, v153
	v_sub_f32_e32 v159, v199, v143
	v_sub_f32_e32 v158, v159, v142
	v_sub_f32_e32 v157, v158, v141
	v_sub_f32_e32 v156, v157, v140
	v_add_f32_e32 v44, v44, v156
	v_add_f32_e32 v45, v45, v157
	v_add_f32_e32 v46, v46, v158
	v_add_f32_e32 v47, v47, v159
	v_exp_f32_e32 v44, v44
	v_exp_f32_e32 v45, v45
	v_exp_f32_e32 v46, v46
	v_exp_f32_e32 v47, v47
	s_waitcnt lgkmcnt(2)
	v_and_b32_e32 v152, v116, v125
	v_add_f32_e32 v153, v121, v125
	v_sub_f32_e32 v199, v127, v152
	v_sub_f32_e32 v127, v127, v153
	v_sub_f32_e32 v159, v199, v139
	v_sub_f32_e32 v158, v159, v138
	v_sub_f32_e32 v157, v158, v137
	v_sub_f32_e32 v156, v157, v136
	v_add_f32_e32 v40, v40, v156
	v_add_f32_e32 v41, v41, v157
	v_add_f32_e32 v42, v42, v158
	v_add_f32_e32 v43, v43, v159
	v_exp_f32_e32 v40, v40
	v_exp_f32_e32 v41, v41
	v_exp_f32_e32 v42, v42
	v_exp_f32_e32 v43, v43
	s_waitcnt lgkmcnt(1)
	v_and_b32_e32 v152, v116, v124
	v_add_f32_e32 v153, v120, v124
	v_sub_f32_e32 v199, v127, v152
	v_sub_f32_e32 v127, v127, v153
	v_sub_f32_e32 v159, v199, v135
	v_sub_f32_e32 v158, v159, v134
	v_sub_f32_e32 v157, v158, v133
	v_sub_f32_e32 v156, v157, v132
	v_add_f32_e32 v36, v36, v156
	v_add_f32_e32 v37, v37, v157
	v_add_f32_e32 v38, v38, v158
	v_add_f32_e32 v39, v39, v159
	v_exp_f32_e32 v36, v36
	v_exp_f32_e32 v37, v37
	v_exp_f32_e32 v38, v38
	v_exp_f32_e32 v39, v39
	s_waitcnt lgkmcnt(0)
	v_and_b32_e32 v152, v116, v123
	v_add_f32_e32 v153, v119, v123
	v_sub_f32_e32 v199, v127, v152
	v_sub_f32_e32 v127, v127, v153
	v_sub_f32_e32 v159, v199, v131
	v_sub_f32_e32 v158, v159, v130
	v_sub_f32_e32 v157, v158, v129
	v_sub_f32_e32 v156, v157, v128
	v_add_f32_e32 v32, v32, v156
	v_add_f32_e32 v33, v33, v157
	v_add_f32_e32 v34, v34, v158
	v_add_f32_e32 v35, v35, v159
	v_exp_f32_e32 v32, v32
	v_exp_f32_e32 v33, v33
	v_exp_f32_e32 v34, v34
	v_exp_f32_e32 v35, v35
	v_cvt_pk_bf16_f32 v144, v32, v33
	v_cvt_pk_bf16_f32 v145, v34, v35
	v_cvt_pk_bf16_f32 v146, v36, v37
	v_cvt_pk_bf16_f32 v147, v38, v39
	v_cvt_pk_bf16_f32 v148, v40, v41
	v_cvt_pk_bf16_f32 v149, v42, v43
	v_cvt_pk_bf16_f32 v150, v44, v45
	v_cvt_pk_bf16_f32 v151, v46, v47
	v_cmp_gt_f32_e32 vcc, 0xc3177ba5, v127
	s_waitcnt vmcnt(0)
	v_mfma_f32_32x32x16_bf16 v[16:31], v[98:101], v[144:147], v[16:31]
	v_mfma_f32_32x32x16_bf16 v[0:15], v[102:105], v[144:147], v[0:15]
	v_mfma_f32_32x32x16_bf16 v[16:31], v[106:109], v[148:151], v[16:31]
	v_mfma_f32_32x32x16_bf16 v[0:15], v[110:113], v[148:151], v[0:15]
	s_cmp_eq_u64 vcc, exec
	s_cselect_b32 s0, 1, 0
	s_cmp_eq_u32 s12, 0
	s_cselect_b32 s1, 1, 0
	s_or_b32 s0, s0, s1
	s_sub_i32 s12, s12, 1
	s_cmp_lg_u32 s0, 0
	s_cbranch_scc0 .Lsb_loop

.LBB0_437:
	s_or_b64 exec, exec, s[0:1]
	v_readfirstlane_b32 s3, v60
	s_cmpk_lt_u32 s3, 0x100
	s_cbranch_scc1 .Ltpdq_skip
	v_mov_b32_e32 v248, v60
	v_mov_b32_e32 v249, v66
	v_mov_b32_e32 v250, v68
	s_add_u32 s0, s54, 0x2a080000
	s_addc_u32 s1, s55, 0
	s_add_u32 s26, s54, 0x2b080000
	s_addc_u32 s27, s55, 0
	s_add_u32 s28, s54, 0x2c080000
	s_addc_u32 s29, s55, 0
	s_lshl_b32 vcc_lo, s84, 6
	s_lshr_b32 vcc_hi, s84, 5
	v_and_b32_e32 v177, 63, v186
	v_lshrrev_b32_e32 v179, 6, v186
	v_and_b32_e32 v179, 3, v179
	v_lshl_add_u32 v178, v179, 4, vcc_lo
	v_mul_u32_u24_e32 v183, s66, v178
	v_lshl_add_u32 v183, v177, 4, v183
	v_add_u32_e32 v183, 0x1e30, v183
	v_lshlrev_b32_e32 v174, 10, v178
	v_lshl_add_u32 v174, v177, 4, v174
	v_and_b32_e32 v180, 0x7ff, v178
	v_lshrrev_b32_e32 v181, 3, v177
	v_lshl_add_u32 v181, vcc_hi, 3, v181
	v_lshlrev_b32_e32 v181, 6, v181
	v_lshrrev_b32_e32 v182, 5, v180
	v_add_u32_e32 v181, v181, v182
	v_lshlrev_b32_e32 v175, 12, v181
	v_bfe_u32 v181, v177, 1, 2
	v_lshlrev_b32_e32 v181, 6, v181
	v_and_b32_e32 v182, 1, v177
	v_lshl_add_u32 v181, v182, 5, v181
	v_and_b32_e32 v182, 31, v180
	v_add_u32_e32 v181, v181, v182
	v_lshl_add_u32 v175, v181, 4, v175
	v_lshrrev_b32_e32 v181, 3, v177
	v_lshl_add_u32 v181, vcc_hi, 3, v181
	v_lshlrev_b32_e32 v181, 7, v181
	v_lshrrev_b32_e32 v182, 4, v180
	v_add_u32_e32 v181, v181, v182
	v_lshlrev_b32_e32 v181, 6, v181
	v_and_b32_e32 v182, 7, v177
	v_lshl_add_u32 v181, v182, 3, v181
	v_lshlrev_b32_e32 v176, 5, v181
	global_load_dwordx4 v[130:133], v183, s[18:19] offset:1024
	v_add_u32_e32 v183, 0x2c00, v183
	global_load_dwordx4 v[134:137], v183, s[18:19] offset:1024
	v_add_u32_e32 v183, 0x2c00, v183
	global_load_dwordx4 v[138:141], v183, s[18:19] offset:1024
	v_add_u32_e32 v183, 0x2c00, v183
	global_load_dwordx4 v[150:153], v183, s[18:19] offset:1024
	v_add_u32_e32 v183, 0x2c00, v183
	global_load_dwordx4 v[154:157], v183, s[18:19] offset:1024
	v_add_u32_e32 v183, 0x2c00, v183
	global_load_dwordx4 v[158:161], v183, s[18:19] offset:1024
	v_add_u32_e32 v183, 0x2c00, v183
	global_load_dwordx4 v[200:203], v183, s[18:19] offset:1024
	v_add_u32_e32 v183, 0x2c00, v183
	global_load_dwordx4 v[204:207], v183, s[18:19] offset:1024
	v_add_u32_e32 v183, 0x2c00, v183
	global_load_dwordx4 v[208:211], v183, s[18:19] offset:1024
	v_add_u32_e32 v183, 0x2c00, v183
	global_load_dwordx4 v[212:215], v183, s[18:19] offset:1024
	v_add_u32_e32 v183, 0x2c00, v183
	global_load_dwordx4 v[216:219], v183, s[18:19] offset:1024
	v_add_u32_e32 v183, 0x2c00, v183
	global_load_dwordx4 v[220:223], v183, s[18:19] offset:1024
	v_add_u32_e32 v183, 0x2c00, v183
	global_load_dwordx4 v[224:227], v183, s[18:19] offset:1024
	v_add_u32_e32 v183, 0x2c00, v183
	global_load_dwordx4 v[228:231], v183, s[18:19] offset:1024
	v_add_u32_e32 v183, 0x2c00, v183
	global_load_dwordx4 v[232:235], v183, s[18:19] offset:1024
	v_add_u32_e32 v183, 0x2c00, v183
	global_load_dwordx4 v[236:239], v183, s[18:19] offset:1024
	v_subrev_u32_e32 v183, 0x29400, v183
	global_load_dwordx4 v[0:3], v183, s[18:19] offset:2048
	v_add_u32_e32 v183, 0x2c00, v183
	global_load_dwordx4 v[4:7], v183, s[18:19] offset:2048
	v_add_u32_e32 v183, 0x2c00, v183
	global_load_dwordx4 v[8:11], v183, s[18:19] offset:2048
	v_add_u32_e32 v183, 0x2c00, v183
	global_load_dwordx4 v[12:15], v183, s[18:19] offset:2048
	v_add_u32_e32 v183, 0x2c00, v183
	global_load_dwordx4 v[16:19], v183, s[18:19] offset:2048
	v_add_u32_e32 v183, 0x2c00, v183
	global_load_dwordx4 v[20:23], v183, s[18:19] offset:2048
	v_add_u32_e32 v183, 0x2c00, v183
	global_load_dwordx4 v[24:27], v183, s[18:19] offset:2048
	v_add_u32_e32 v183, 0x2c00, v183
	global_load_dwordx4 v[28:31], v183, s[18:19] offset:2048
	v_add_u32_e32 v183, 0x2c00, v183
	global_load_dwordx4 v[32:35], v183, s[18:19] offset:2048
	v_add_u32_e32 v183, 0x2c00, v183
	global_load_dwordx4 v[36:39], v183, s[18:19] offset:2048
	v_add_u32_e32 v183, 0x2c00, v183
	global_load_dwordx4 v[40:43], v183, s[18:19] offset:2048
	v_add_u32_e32 v183, 0x2c00, v183
	global_load_dwordx4 v[44:47], v183, s[18:19] offset:2048
	v_add_u32_e32 v183, 0x2c00, v183
	global_load_dwordx4 v[48:51], v183, s[18:19] offset:2048
	v_add_u32_e32 v183, 0x2c00, v183
	global_load_dwordx4 v[52:55], v183, s[18:19] offset:2048
	v_add_u32_e32 v183, 0x2c00, v183
	global_load_dwordx4 v[56:59], v183, s[18:19] offset:2048
	v_add_u32_e32 v183, 0x2c00, v183
	global_load_dwordx4 v[60:63], v183, s[18:19] offset:2048
	s_mov_b32 s2, 0x05040100
	s_mov_b32 s3, 0x07060302
	s_waitcnt vmcnt(31)
	global_store_dwordx4 v175, v[130:133], s[26:27]
	s_waitcnt vmcnt(31)
	global_store_dwordx4 v175, v[134:137], s[26:27] offset:16
	s_waitcnt vmcnt(31)
	global_store_dwordx4 v175, v[138:141], s[26:27] offset:32
	s_waitcnt vmcnt(31)
	global_store_dwordx4 v175, v[150:153], s[26:27] offset:48
	s_waitcnt vmcnt(31)
	global_store_dwordx4 v175, v[154:157], s[26:27] offset:64
	s_waitcnt vmcnt(31)
	global_store_dwordx4 v175, v[158:161], s[26:27] offset:80
	s_waitcnt vmcnt(31)
	global_store_dwordx4 v175, v[200:203], s[26:27] offset:96
	s_waitcnt vmcnt(31)
	global_store_dwordx4 v175, v[204:207], s[26:27] offset:112
	s_waitcnt vmcnt(31)
	global_store_dwordx4 v175, v[208:211], s[26:27] offset:128
	s_waitcnt vmcnt(31)
	global_store_dwordx4 v175, v[212:215], s[26:27] offset:144
	s_waitcnt vmcnt(31)
	global_store_dwordx4 v175, v[216:219], s[26:27] offset:160
	s_waitcnt vmcnt(31)
	global_store_dwordx4 v175, v[220:223], s[26:27] offset:176
	s_waitcnt vmcnt(31)
	global_store_dwordx4 v175, v[224:227], s[26:27] offset:192
	s_waitcnt vmcnt(31)
	global_store_dwordx4 v175, v[228:231], s[26:27] offset:208
	s_waitcnt vmcnt(31)
	global_store_dwordx4 v175, v[232:235], s[26:27] offset:224
	s_waitcnt vmcnt(31)
	global_store_dwordx4 v175, v[236:239], s[26:27] offset:240
	s_waitcnt vmcnt(16)
	s_nop 1
	v_perm_b32 v66, v4, v0, s2
	v_perm_b32 v67, v12, v8, s2
	v_perm_b32 v68, v36, v32, s2
	v_perm_b32 v69, v44, v40, s2
	v_perm_b32 v70, v20, v16, s2
	v_perm_b32 v71, v28, v24, s2
	v_perm_b32 v72, v52, v48, s2
	v_perm_b32 v73, v60, v56, s2
	global_store_dwordx4 v176, v[66:69], s[28:29]
	global_store_dwordx4 v176, v[70:73], s[28:29] offset:16
	v_perm_b32 v74, v4, v0, s3
	v_perm_b32 v75, v12, v8, s3
	v_perm_b32 v76, v36, v32, s3
	v_perm_b32 v77, v44, v40, s3
	v_perm_b32 v78, v20, v16, s3
	v_perm_b32 v79, v28, v24, s3
	v_perm_b32 v80, v52, v48, s3
	v_perm_b32 v81, v60, v56, s3
	global_store_dwordx4 v176, v[74:77], s[28:29] offset:32
	global_store_dwordx4 v176, v[78:81], s[28:29] offset:48
	v_perm_b32 v66, v5, v1, s2
	v_perm_b32 v67, v13, v9, s2
	v_perm_b32 v68, v37, v33, s2
	v_perm_b32 v69, v45, v41, s2
	v_perm_b32 v70, v21, v17, s2
	v_perm_b32 v71, v29, v25, s2
	v_perm_b32 v72, v53, v49, s2
	v_perm_b32 v73, v61, v57, s2
	global_store_dwordx4 v176, v[66:69], s[28:29] offset:64
	global_store_dwordx4 v176, v[70:73], s[28:29] offset:80
	v_perm_b32 v74, v5, v1, s3
	v_perm_b32 v75, v13, v9, s3
	v_perm_b32 v76, v37, v33, s3
	v_perm_b32 v77, v45, v41, s3
	v_perm_b32 v78, v21, v17, s3
	v_perm_b32 v79, v29, v25, s3
	v_perm_b32 v80, v53, v49, s3
	v_perm_b32 v81, v61, v57, s3
	global_store_dwordx4 v176, v[74:77], s[28:29] offset:96
	global_store_dwordx4 v176, v[78:81], s[28:29] offset:112
	v_perm_b32 v66, v6, v2, s2
	v_perm_b32 v67, v14, v10, s2
	v_perm_b32 v68, v38, v34, s2
	v_perm_b32 v69, v46, v42, s2
	v_perm_b32 v70, v22, v18, s2
	v_perm_b32 v71, v30, v26, s2
	v_perm_b32 v72, v54, v50, s2
	v_perm_b32 v73, v62, v58, s2
	global_store_dwordx4 v176, v[66:69], s[28:29] offset:128
	global_store_dwordx4 v176, v[70:73], s[28:29] offset:144
	v_perm_b32 v74, v6, v2, s3
	v_perm_b32 v75, v14, v10, s3
	v_perm_b32 v76, v38, v34, s3
	v_perm_b32 v77, v46, v42, s3
	v_perm_b32 v78, v22, v18, s3
	v_perm_b32 v79, v30, v26, s3
	v_perm_b32 v80, v54, v50, s3
	v_perm_b32 v81, v62, v58, s3
	global_store_dwordx4 v176, v[74:77], s[28:29] offset:160
	global_store_dwordx4 v176, v[78:81], s[28:29] offset:176
	v_perm_b32 v66, v7, v3, s2
	v_perm_b32 v67, v15, v11, s2
	v_perm_b32 v68, v39, v35, s2
	v_perm_b32 v69, v47, v43, s2
	v_perm_b32 v70, v23, v19, s2
	v_perm_b32 v71, v31, v27, s2
	v_perm_b32 v72, v55, v51, s2
	v_perm_b32 v73, v63, v59, s2
	global_store_dwordx4 v176, v[66:69], s[28:29] offset:192
	global_store_dwordx4 v176, v[70:73], s[28:29] offset:208
	v_perm_b32 v74, v7, v3, s3
	v_perm_b32 v75, v15, v11, s3
	v_perm_b32 v76, v39, v35, s3
	v_perm_b32 v77, v47, v43, s3
	v_perm_b32 v78, v23, v19, s3
	v_perm_b32 v79, v31, v27, s3
	v_perm_b32 v80, v55, v51, s3
	v_perm_b32 v81, v63, v59, s3
	global_store_dwordx4 v176, v[74:77], s[28:29] offset:224
	global_store_dwordx4 v176, v[78:81], s[28:29] offset:240
	v_mov_b32_e32 v60, v248
	v_mov_b32_e32 v66, v249
	v_mov_b32_e32 v68, v250
